# V^T epilogue: one exact 1/sqrt chain per lane (token #fr) + DPP row broadcast instead of 16 redundant chains per lane
# speedup vs baseline: 1.0115x; 1.0011x over previous
.LBB0_216:
	v_lshl_or_b32 v162, s58, 8, v181
	v_ashrrev_i32_e32 v163, 31, v162
	v_and_b32_e32 v192, 15, v218
	v_and_b32_e32 v193, 8, v192
	v_and_b32_e32 v192, 7, v192
	v_lshl_add_u32 v192, v193, 4, v192
	v_add_u32_e32 v192, v162, v192
	v_ashrrev_i32_e32 v193, 31, v192
	v_lshl_add_u64 v[192:193], v[192:193], 4, s[6:7]
	global_load_dwordx4 v[186:189], v[192:193], off
	s_mov_b32 s14, 0xf800000
	s_waitcnt vmcnt(0)
	v_mov_b32_e32 v190, v187
	v_mov_b32_e32 v191, v188
	v_mov_b32_e32 v187, v189
	v_pk_add_f32 v[186:187], v[190:191], v[186:187]
	s_nop 1
	v_add_f32_e32 v186, v186, v187
	v_fmamk_f32 v186, v186, 0x3a800000, v215
	v_cmp_gt_f32_e32 vcc, s14, v186
	v_mul_f32_e32 v187, 0x4f800000, v186
	s_nop 1
	v_cndmask_b32_e32 v186, v186, v187, vcc
	v_sqrt_f32_e32 v187, v186
	s_nop 1
	v_add_u32_e32 v188, -1, v187
	v_fma_f32 v189, -v188, v187, v186
	v_cmp_ge_f32_e64 s[4:5], 0, v189
	v_add_u32_e32 v189, 1, v187
	s_nop 1
	v_cndmask_b32_e64 v188, v187, v188, s[4:5]
	v_fma_f32 v187, -v189, v187, v186
	v_cmp_lt_f32_e64 s[4:5], 0, v187
	s_nop 1
	v_cndmask_b32_e64 v187, v188, v189, s[4:5]
	v_mul_f32_e32 v188, 0x37800000, v187
	v_cndmask_b32_e32 v187, v187, v188, vcc
	v_cmp_class_f32_e32 vcc, v186, v216
	s_nop 1
	v_cndmask_b32_e32 v186, v187, v186, vcc
	v_div_scale_f32 v187, s[4:5], v186, v186, 1.0
	v_rcp_f32_e32 v188, v187
	s_nop 1
	v_fma_f32 v189, -v187, v188, 1.0
	v_fmac_f32_e32 v188, v189, v188
	v_div_scale_f32 v189, vcc, 1.0, v186, 1.0
	v_mul_f32_e32 v190, v189, v188
	v_fma_f32 v191, -v187, v190, v189
	v_fmac_f32_e32 v190, v191, v188
	v_fma_f32 v187, -v187, v190, v189
	v_div_fmas_f32 v187, v187, v188, v190
	v_div_fixup_f32 v190, v187, v186, 1.0
	v_mov_b32_e32 v233, v190
	s_nop 1
	s_waitcnt vmcnt(8)
	s_nop 1
	v_mov_b32_dpp v158, v233 row_newbcast:0 row_mask:0xf bank_mask:0xf
	s_nop 1
	v_mov_b32_dpp v159, v233 row_newbcast:1 row_mask:0xf bank_mask:0xf
	v_pk_mul_f32 v[128:129], v[128:129], v[158:159]
	v_pk_mul_f32 v[116:117], v[116:117], v[158:159]
	v_pk_mul_f32 v[100:101], v[100:101], v[158:159]
	v_pk_mul_f32 v[84:85], v[84:85], v[158:159]
	v_pk_mul_f32 v[64:65], v[64:65], v[158:159]
	v_pk_mul_f32 v[52:53], v[52:53], v[158:159]
	v_pk_mul_f32 v[36:37], v[36:37], v[158:159]
	v_pk_mul_f32 v[20:21], v[20:21], v[158:159]
	s_nop 1
	v_mov_b32_dpp v160, v233 row_newbcast:2 row_mask:0xf bank_mask:0xf
	s_nop 1
	v_mov_b32_dpp v161, v233 row_newbcast:3 row_mask:0xf bank_mask:0xf
	v_pk_mul_f32 v[130:131], v[130:131], v[160:161]
	v_pk_mul_f32 v[66:67], v[66:67], v[160:161]
	s_waitcnt vmcnt(4)
	s_nop 1
	v_mov_b32_dpp v164, v233 row_newbcast:4 row_mask:0xf bank_mask:0xf
	s_nop 1
	v_mov_b32_dpp v165, v233 row_newbcast:5 row_mask:0xf bank_mask:0xf
	s_nop 1
	v_mov_b32_dpp v166, v233 row_newbcast:6 row_mask:0xf bank_mask:0xf
	s_nop 1
	v_mov_b32_dpp v167, v233 row_newbcast:7 row_mask:0xf bank_mask:0xf
	s_waitcnt vmcnt(4)
	s_nop 1
	v_mov_b32_dpp v176, v233 row_newbcast:8 row_mask:0xf bank_mask:0xf
	s_nop 1
	v_mov_b32_dpp v177, v233 row_newbcast:9 row_mask:0xf bank_mask:0xf
	v_pk_mul_f32 v[120:121], v[120:121], v[176:177]
	v_pk_mul_f32 v[104:105], v[104:105], v[176:177]
	v_pk_mul_f32 v[88:89], v[88:89], v[176:177]
	v_pk_mul_f32 v[72:73], v[72:73], v[176:177]
	v_pk_mul_f32 v[56:57], v[56:57], v[176:177]
	v_pk_mul_f32 v[40:41], v[40:41], v[176:177]
	v_pk_mul_f32 v[24:25], v[24:25], v[176:177]
	v_pk_mul_f32 v[8:9], v[8:9], v[176:177]
	s_nop 1
	v_mov_b32_dpp v178, v233 row_newbcast:10 row_mask:0xf bank_mask:0xf
	s_nop 1
	v_mov_b32_dpp v179, v233 row_newbcast:11 row_mask:0xf bank_mask:0xf
	v_pk_mul_f32 v[122:123], v[122:123], v[178:179]
	v_pk_mul_f32 v[106:107], v[106:107], v[178:179]
	v_pk_mul_f32 v[90:91], v[90:91], v[178:179]
	v_pk_mul_f32 v[74:75], v[74:75], v[178:179]
	v_pk_mul_f32 v[58:59], v[58:59], v[178:179]
	v_pk_mul_f32 v[42:43], v[42:43], v[178:179]
	v_pk_mul_f32 v[26:27], v[26:27], v[178:179]
	v_pk_mul_f32 v[10:11], v[10:11], v[178:179]
	s_waitcnt vmcnt(0)
	s_nop 1
	v_mov_b32_dpp v144, v233 row_newbcast:12 row_mask:0xf bank_mask:0xf
	s_nop 1
	v_mov_b32_dpp v145, v233 row_newbcast:13 row_mask:0xf bank_mask:0xf
	s_nop 1
	v_mov_b32_dpp v136, v233 row_newbcast:14 row_mask:0xf bank_mask:0xf
	v_pk_mul_f32 v[140:141], v[126:127], v[166:167]
	v_pk_mul_f32 v[126:127], v[124:125], v[164:165]
	v_cvt_pk_bf16_f32 v124, v128, v129
	v_cvt_pk_bf16_f32 v125, v130, v131
	v_cvt_pk_bf16_f32 v126, v126, v127
	v_cvt_pk_bf16_f32 v127, v140, v141
	s_nop 1
	s_mov_b64 s[4:5], 0x400000
	v_lshl_add_u32 v134, s46, 8, v1
	v_ashrrev_i32_e32 v135, 31, v134
	v_mov_b32_dpp v137, v233 row_newbcast:15 row_mask:0xf bank_mask:0xf
	v_lshlrev_b64 v[132:133], 15, v[134:135]
	v_lshl_add_u64 v[132:133], s[22:23], 0, v[132:133]
	v_lshlrev_b64 v[138:139], 1, v[162:163]
	v_lshl_add_u64 v[132:133], v[132:133], 0, v[138:139]
	global_store_dwordx4 v[132:133], v[124:127], off
	s_nop 1
	v_pk_mul_f32 v[124:125], v[114:115], v[136:137]
	v_pk_mul_f32 v[114:115], v[112:113], v[144:145]
	v_cvt_pk_bf16_f32 v112, v120, v121
	v_cvt_pk_bf16_f32 v113, v122, v123
	s_nop 1
	v_cvt_pk_bf16_f32 v114, v114, v115
	v_cvt_pk_bf16_f32 v115, v124, v125
	global_store_dwordx4 v[132:133], v[112:115], off offset:256
	s_nop 1
	v_or_b32_e32 v112, 16, v134
	v_ashrrev_i32_e32 v113, 31, v112
	v_lshlrev_b64 v[112:113], 15, v[112:113]
	v_lshl_add_u64 v[112:113], s[22:23], 0, v[112:113]
	v_lshl_add_u64 v[112:113], v[112:113], 0, v[138:139]
	v_pk_mul_f32 v[114:115], v[118:119], v[160:161]
	v_pk_mul_f32 v[118:119], v[110:111], v[166:167]
	v_pk_mul_f32 v[110:111], v[108:109], v[164:165]
	v_cvt_pk_bf16_f32 v108, v116, v117
	v_cvt_pk_bf16_f32 v109, v114, v115
	s_nop 1
	v_cvt_pk_bf16_f32 v110, v110, v111
	v_cvt_pk_bf16_f32 v111, v118, v119
	global_store_dwordx4 v[112:113], v[108:111], off
	s_nop 1
	v_pk_mul_f32 v[108:109], v[98:99], v[136:137]
	v_pk_mul_f32 v[98:99], v[96:97], v[144:145]
	v_cvt_pk_bf16_f32 v96, v104, v105
	v_cvt_pk_bf16_f32 v97, v106, v107
	s_nop 1
	v_cvt_pk_bf16_f32 v98, v98, v99
	v_cvt_pk_bf16_f32 v99, v108, v109
	global_store_dwordx4 v[112:113], v[96:99], off offset:256
	s_nop 1
	v_or_b32_e32 v96, 32, v134
	v_ashrrev_i32_e32 v97, 31, v96
	v_lshlrev_b64 v[96:97], 15, v[96:97]
	v_lshl_add_u64 v[96:97], s[22:23], 0, v[96:97]
	v_lshl_add_u64 v[96:97], v[96:97], 0, v[138:139]
	v_pk_mul_f32 v[98:99], v[102:103], v[160:161]
	v_pk_mul_f32 v[102:103], v[94:95], v[166:167]
	v_pk_mul_f32 v[94:95], v[92:93], v[164:165]
	v_cvt_pk_bf16_f32 v92, v100, v101
	v_cvt_pk_bf16_f32 v93, v98, v99
	s_nop 1
	v_cvt_pk_bf16_f32 v94, v94, v95
	v_cvt_pk_bf16_f32 v95, v102, v103
	global_store_dwordx4 v[96:97], v[92:95], off
	s_nop 1
	v_pk_mul_f32 v[92:93], v[82:83], v[136:137]
	v_pk_mul_f32 v[82:83], v[80:81], v[144:145]
	v_cvt_pk_bf16_f32 v80, v88, v89
	v_cvt_pk_bf16_f32 v81, v90, v91
	s_nop 1
	v_cvt_pk_bf16_f32 v82, v82, v83
	v_cvt_pk_bf16_f32 v83, v92, v93
	global_store_dwordx4 v[96:97], v[80:83], off offset:256
	s_nop 1
	v_or_b32_e32 v80, 48, v134
	v_ashrrev_i32_e32 v81, 31, v80
	v_lshlrev_b64 v[80:81], 15, v[80:81]
	v_lshl_add_u64 v[80:81], s[22:23], 0, v[80:81]
	v_lshl_add_u64 v[80:81], v[80:81], 0, v[138:139]
	v_pk_mul_f32 v[82:83], v[86:87], v[160:161]
	v_pk_mul_f32 v[86:87], v[78:79], v[166:167]
	v_pk_mul_f32 v[78:79], v[76:77], v[164:165]
	v_cvt_pk_bf16_f32 v76, v84, v85
	v_cvt_pk_bf16_f32 v77, v82, v83
	s_nop 1
	v_cvt_pk_bf16_f32 v78, v78, v79
	v_cvt_pk_bf16_f32 v79, v86, v87
	global_store_dwordx4 v[80:81], v[76:79], off
	s_nop 1
	v_pk_mul_f32 v[76:77], v[70:71], v[136:137]
	v_pk_mul_f32 v[70:71], v[68:69], v[144:145]
	v_cvt_pk_bf16_f32 v68, v72, v73
	v_cvt_pk_bf16_f32 v69, v74, v75
	s_nop 1
	v_cvt_pk_bf16_f32 v70, v70, v71
	v_cvt_pk_bf16_f32 v71, v76, v77
	global_store_dwordx4 v[80:81], v[68:71], off offset:256
	s_nop 1
	v_lshl_add_u64 v[68:69], v[132:133], 0, s[4:5]
	s_mov_b32 s4, 0x400000
	v_pk_mul_f32 v[70:71], v[62:63], v[166:167]
	v_pk_mul_f32 v[62:63], v[60:61], v[164:165]
	v_cvt_pk_bf16_f32 v60, v64, v65
	v_add_co_u32_e32 v64, vcc, s4, v132
	v_cvt_pk_bf16_f32 v61, v66, v67
	v_cvt_pk_bf16_f32 v62, v62, v63
	v_cvt_pk_bf16_f32 v63, v70, v71
	s_mov_b64 s[4:5], 0x480000
	s_nop 1
	v_addc_co_u32_e32 v65, vcc, 0, v133, vcc
	global_store_dwordx4 v[64:65], v[60:63], off
	s_nop 1
	v_pk_mul_f32 v[60:61], v[50:51], v[136:137]
	v_pk_mul_f32 v[50:51], v[48:49], v[144:145]
	v_cvt_pk_bf16_f32 v48, v56, v57
	v_cvt_pk_bf16_f32 v49, v58, v59
	s_nop 1
	v_cvt_pk_bf16_f32 v50, v50, v51
	v_cvt_pk_bf16_f32 v51, v60, v61
	global_store_dwordx4 v[68:69], v[48:51], off offset:256
	s_nop 1
	v_lshl_add_u64 v[48:49], v[132:133], 0, s[4:5]
	v_pk_mul_f32 v[50:51], v[54:55], v[160:161]
	s_mov_b32 s4, 0x480000
	v_pk_mul_f32 v[54:55], v[46:47], v[166:167]
	v_pk_mul_f32 v[46:47], v[44:45], v[164:165]
	v_cvt_pk_bf16_f32 v44, v52, v53
	v_cvt_pk_bf16_f32 v45, v50, v51
	v_add_co_u32_e32 v50, vcc, s4, v132
	v_cvt_pk_bf16_f32 v46, v46, v47
	v_cvt_pk_bf16_f32 v47, v54, v55
	s_mov_b64 s[4:5], 0x500000
	s_nop 1
	v_addc_co_u32_e32 v51, vcc, 0, v133, vcc
	global_store_dwordx4 v[50:51], v[44:47], off
	s_nop 1
	v_pk_mul_f32 v[44:45], v[34:35], v[136:137]
	v_pk_mul_f32 v[34:35], v[32:33], v[144:145]
	v_cvt_pk_bf16_f32 v32, v40, v41
	v_cvt_pk_bf16_f32 v33, v42, v43
	s_nop 1
	v_cvt_pk_bf16_f32 v34, v34, v35
	v_cvt_pk_bf16_f32 v35, v44, v45
	global_store_dwordx4 v[48:49], v[32:35], off offset:256
	s_nop 1
	v_lshl_add_u64 v[32:33], v[132:133], 0, s[4:5]
	v_pk_mul_f32 v[34:35], v[38:39], v[160:161]
	s_mov_b32 s4, 0x500000
	v_pk_mul_f32 v[38:39], v[30:31], v[166:167]
	v_pk_mul_f32 v[30:31], v[28:29], v[164:165]
	v_cvt_pk_bf16_f32 v28, v36, v37
	v_cvt_pk_bf16_f32 v29, v34, v35
	v_add_co_u32_e32 v34, vcc, s4, v132
	v_cvt_pk_bf16_f32 v30, v30, v31
	v_cvt_pk_bf16_f32 v31, v38, v39
	s_mov_b64 s[4:5], 0x580000
	s_nop 1
	v_addc_co_u32_e32 v35, vcc, 0, v133, vcc
	global_store_dwordx4 v[34:35], v[28:31], off
	s_nop 1
	v_pk_mul_f32 v[28:29], v[18:19], v[136:137]
	v_pk_mul_f32 v[18:19], v[16:17], v[144:145]
	v_cvt_pk_bf16_f32 v16, v24, v25
	v_cvt_pk_bf16_f32 v17, v26, v27
	s_nop 1
	v_cvt_pk_bf16_f32 v18, v18, v19
	v_cvt_pk_bf16_f32 v19, v28, v29
	global_store_dwordx4 v[32:33], v[16:19], off offset:256
	s_nop 1
	v_lshl_add_u64 v[16:17], v[132:133], 0, s[4:5]
	v_pk_mul_f32 v[18:19], v[22:23], v[160:161]
	s_mov_b32 s4, 0x580000
	v_pk_mul_f32 v[22:23], v[14:15], v[166:167]
	v_pk_mul_f32 v[14:15], v[12:13], v[164:165]
	v_cvt_pk_bf16_f32 v12, v20, v21
	v_cvt_pk_bf16_f32 v13, v18, v19
	v_add_co_u32_e32 v18, vcc, s4, v132
	v_cvt_pk_bf16_f32 v14, v14, v15
	v_cvt_pk_bf16_f32 v15, v22, v23
	s_mov_b64 s[4:5], -1
	s_nop 1
	v_addc_co_u32_e32 v19, vcc, 0, v133, vcc
	global_store_dwordx4 v[18:19], v[12:15], off
	s_andn2_b64 vcc, exec, s[28:29]
	s_nop 1
	v_pk_mul_f32 v[12:13], v[6:7], v[136:137]
	v_pk_mul_f32 v[6:7], v[4:5], v[144:145]
	v_cvt_pk_bf16_f32 v4, v8, v9
	v_cvt_pk_bf16_f32 v5, v10, v11
	s_nop 1
	v_cvt_pk_bf16_f32 v6, v6, v7
	v_cvt_pk_bf16_f32 v7, v12, v13
	global_store_dwordx4 v[16:17], v[4:7], off offset:256
	s_cbranch_vccnz .LBB0_205
	s_andn2_b64 vcc, exec, s[24:25]
	s_cbranch_vccnz .LBB0_204
	s_barrier
	s_branch .LBB0_204
